# window attention: key tiles lying fully inside every row's window skip the two mask blocks (wave-uniform test)
# speedup vs baseline: 1.0012x; 1.0012x over previous
.LBB0_121:
	s_and_saveexec_b64 s[44:45], s[8:9]
	s_cbranch_execz .LBB0_131
	s_bitcmp1_b32 s49, 0
	s_cselect_b32 s8, 0x4800, 0
	s_add_i32 s8, s8, 16
	v_add3_u32 v0, s8, v186, v224
	ds_read_b128 v[2:5], v0
	s_and_b64 s[2:3], s[16:17], s[2:3]
	v_add_u32_e32 v6, 64, v230
	v_cmp_ge_i32_e64 s[98:99], s48, v6
	v_add_u32_e32 v6, 0xffffff81, v231
	v_cmp_le_i32_e64 s[100:101], s48, v6
	s_nop 1
	s_and_b64 s[98:99], s[98:99], s[100:101]
	s_andn2_b64 s[2:3], s[2:3], s[98:99]
	v_cndmask_b32_e64 v6, 0, 1, s[2:3]
	v_cmp_ne_u32_e64 s[38:39], 1, v6
	s_andn2_b64 vcc, exec, s[2:3]
	ds_read_b128 v[6:9], v0 offset:32
	ds_read_b128 v[10:13], v0 offset:64
	s_waitcnt lgkmcnt(2)
	v_mfma_f32_32x32x16_bf16 v[112:127], v[2:5], v[144:147], v[234:249]
	v_mfma_f32_32x32x16_bf16 v[96:111], v[2:5], v[160:163], v[188:203]
	ds_read_b128 v[2:5], v0 offset:96
	s_waitcnt lgkmcnt(2)
	v_mfma_f32_32x32x16_bf16 v[112:127], v[6:9], v[148:151], v[112:127]
	v_mfma_f32_32x32x16_bf16 v[96:111], v[6:9], v[164:167], v[96:111]
	ds_read_b128 v[6:9], v0 offset:4608
	s_waitcnt lgkmcnt(2)
	v_mfma_f32_32x32x16_bf16 v[112:127], v[10:13], v[152:155], v[112:127]
	v_mfma_f32_32x32x16_bf16 v[96:111], v[10:13], v[168:171], v[96:111]
	ds_read_b128 v[10:13], v0 offset:4640
	s_waitcnt lgkmcnt(2)
	v_mfma_f32_32x32x16_bf16 v[112:127], v[2:5], v[156:159], v[112:127]
	v_mfma_f32_32x32x16_bf16 v[96:111], v[2:5], v[172:175], v[96:111]
	ds_read_b128 v[2:5], v0 offset:4672
	s_waitcnt lgkmcnt(2)
	v_mfma_f32_32x32x16_bf16 v[128:143], v[6:9], v[144:147], v[234:249]
	v_mfma_f32_32x32x16_bf16 v[80:95], v[6:9], v[160:163], v[188:203]
	ds_read_b128 v[6:9], v0 offset:4704
	v_add_u32_e32 v0, s48, v221
	s_waitcnt lgkmcnt(2)
	v_mfma_f32_32x32x16_bf16 v[128:143], v[10:13], v[148:151], v[128:143]
	v_mfma_f32_32x32x16_bf16 v[80:95], v[10:13], v[164:167], v[80:95]
	s_waitcnt lgkmcnt(1)
	v_mfma_f32_32x32x16_bf16 v[128:143], v[2:5], v[152:155], v[128:143]
	v_mfma_f32_32x32x16_bf16 v[80:95], v[2:5], v[168:171], v[80:95]
	s_waitcnt lgkmcnt(0)
	v_mfma_f32_32x32x16_bf16 v[128:143], v[6:9], v[156:159], v[128:143]
	v_mfma_f32_32x32x16_bf16 v[80:95], v[6:9], v[172:175], v[80:95]
	s_cbranch_vccnz .LBB0_124
	v_sub_u32_e32 v2, v0, v229
	s_movk_i32 s0, 0xfefe
	v_cmp_lt_u32_e32 vcc, s0, v2
	v_add_u32_e32 v3, 1, v2
	s_nop 0
	v_cndmask_b32_e32 v112, v210, v112, vcc
	v_cmp_lt_u32_e32 vcc, s0, v3
	v_add_u32_e32 v3, 2, v2
	s_nop 0
	v_cndmask_b32_e32 v113, v210, v113, vcc
	v_cmp_lt_u32_e32 vcc, s0, v3
	v_add_u32_e32 v3, 3, v2
	s_nop 0
	v_cndmask_b32_e32 v114, v210, v114, vcc
	v_cmp_lt_u32_e32 vcc, s0, v3
	v_add_u32_e32 v3, 8, v2
	s_nop 0
	v_cndmask_b32_e32 v115, v210, v115, vcc
	v_cmp_lt_u32_e32 vcc, s0, v3
	v_add_u32_e32 v3, 9, v2
	s_nop 0
	v_cndmask_b32_e32 v116, v210, v116, vcc
	v_cmp_lt_u32_e32 vcc, s0, v3
	v_add_u32_e32 v3, 10, v2
	s_nop 0
	v_cndmask_b32_e32 v117, v210, v117, vcc
	v_cmp_lt_u32_e32 vcc, s0, v3
	v_add_u32_e32 v3, 11, v2
	s_nop 0
	v_cndmask_b32_e32 v118, v210, v118, vcc
	v_cmp_lt_u32_e32 vcc, s0, v3
	v_add_u32_e32 v3, 16, v2
	s_nop 0
	v_cndmask_b32_e32 v119, v210, v119, vcc
	v_cmp_lt_u32_e32 vcc, s0, v3
	v_add_u32_e32 v3, 17, v2
	s_nop 0
	v_cndmask_b32_e32 v120, v210, v120, vcc
	v_cmp_lt_u32_e32 vcc, s0, v3
	v_add_u32_e32 v3, 18, v2
	s_nop 0
	v_cndmask_b32_e32 v121, v210, v121, vcc
	v_cmp_lt_u32_e32 vcc, s0, v3
	v_add_u32_e32 v3, 19, v2
	s_nop 0
	v_cndmask_b32_e32 v122, v210, v122, vcc
	v_cmp_lt_u32_e32 vcc, s0, v3
	v_add_u32_e32 v3, 24, v2
	s_nop 0
	v_cndmask_b32_e32 v123, v210, v123, vcc
	v_cmp_lt_u32_e32 vcc, s0, v3
	v_add_u32_e32 v3, 25, v2
	s_nop 0
	v_cndmask_b32_e32 v124, v210, v124, vcc
	v_cmp_lt_u32_e32 vcc, s0, v3
	v_add_u32_e32 v3, 26, v2
	s_nop 0
	v_cndmask_b32_e32 v125, v210, v125, vcc
	v_cmp_lt_u32_e32 vcc, s0, v3
	v_add_u32_e32 v3, 27, v2
	s_nop 0
	v_cndmask_b32_e32 v126, v210, v126, vcc
	v_cmp_lt_u32_e32 vcc, s0, v3
	v_add_u32_e32 v3, 32, v2
	s_nop 0
	v_cndmask_b32_e32 v127, v210, v127, vcc
	v_cmp_lt_u32_e32 vcc, s0, v3
	v_add_u32_e32 v3, 33, v2
	s_nop 0
	v_cndmask_b32_e32 v128, v210, v128, vcc
	v_cmp_lt_u32_e32 vcc, s0, v3
	v_add_u32_e32 v3, 34, v2
	s_nop 0
	v_cndmask_b32_e32 v129, v210, v129, vcc
	v_cmp_lt_u32_e32 vcc, s0, v3
	v_add_u32_e32 v3, 35, v2
	s_nop 0
	v_cndmask_b32_e32 v130, v210, v130, vcc
	v_cmp_lt_u32_e32 vcc, s0, v3
	v_add_u32_e32 v3, 40, v2
	s_nop 0
	v_cndmask_b32_e32 v131, v210, v131, vcc
	v_cmp_lt_u32_e32 vcc, s0, v3
	v_add_u32_e32 v3, 41, v2
	s_nop 0
	v_cndmask_b32_e32 v132, v210, v132, vcc
	v_cmp_lt_u32_e32 vcc, s0, v3
	v_add_u32_e32 v3, 42, v2
	s_nop 0
	v_cndmask_b32_e32 v133, v210, v133, vcc
	v_cmp_lt_u32_e32 vcc, s0, v3
	v_add_u32_e32 v3, 43, v2
	s_nop 0
	v_cndmask_b32_e32 v134, v210, v134, vcc
	v_cmp_lt_u32_e32 vcc, s0, v3
	v_add_u32_e32 v3, 48, v2
	s_nop 0
	v_cndmask_b32_e32 v135, v210, v135, vcc
	v_cmp_lt_u32_e32 vcc, s0, v3
	v_add_u32_e32 v3, 49, v2
	s_nop 0
	v_cndmask_b32_e32 v136, v210, v136, vcc
	v_cmp_lt_u32_e32 vcc, s0, v3
	v_add_u32_e32 v3, 50, v2
	s_nop 0
	v_cndmask_b32_e32 v137, v210, v137, vcc
	v_cmp_lt_u32_e32 vcc, s0, v3
	v_add_u32_e32 v3, 51, v2
	s_nop 0
	v_cndmask_b32_e32 v138, v210, v138, vcc
	v_cmp_lt_u32_e32 vcc, s0, v3
	v_add_u32_e32 v3, 56, v2
	s_nop 0
	v_cndmask_b32_e32 v139, v210, v139, vcc
	v_cmp_lt_u32_e32 vcc, s0, v3
	v_add_u32_e32 v3, 57, v2
	s_nop 0
	v_cndmask_b32_e32 v140, v210, v140, vcc
	v_cmp_lt_u32_e32 vcc, s0, v3
	v_add_u32_e32 v3, 58, v2
	v_add_u32_e32 v2, 59, v2
	v_cndmask_b32_e32 v141, v210, v141, vcc
	v_cmp_lt_u32_e32 vcc, s0, v3
	s_nop 1
	v_cndmask_b32_e32 v142, v210, v142, vcc
	v_cmp_lt_u32_e32 vcc, s0, v2
	s_nop 1
	v_cndmask_b32_e32 v143, v210, v143, vcc
